# weight-conversion plan: P0 converts only w_in (4608 items), rest moved to P1/P5 tails
# baseline (speedup 1.0000x reference)
; #define LAS __attribute__((address_space(3)))
; __device__ __forceinline__ unsigned cvt_pk_bf16(float lo, float hi) { unsigned r; asm volatile("v_cvt_pk_bf16_f32 %0, %1, %2" : "=v"(r) : "v"(lo), "v"(hi)); return r; }
; template <bool UPPERM> __device__ __forceinline__ void p0_transpose_item(const float* W, int K, int N, bf16_t* WT, const float* gk, LAS float* scr, int item, int lane) {
;     const int nblk = N / 64, kb = item / nblk, nb = item % nblk, k0 = 64 * kb, n0 = 64 * nb;
;     const int dn0 = !UPPERM ? n0 : (n0 < FF ? ((n0 >> 7) * 256 + 2 * (n0 & 127)) : ((((n0 - FF) >> 7) * 256) + 2 * ((n0 - FF) & 127) + 32));
;     const int r4 = lane >> 4, c4 = (lane & 15) * 4;
;     f32x4 v[16];
; #pragma unroll
;     for (int i = 0; i < 16; ++i) v[i] = *(const f32x4*)(W + (size_t)(k0 + 4 * i + r4) * N + n0 + c4);
;     if (gk) {
; #pragma unroll
;         for (int i = 0; i < 16; ++i) v[i] *= gk[k0 + 4 * i + r4];
;     }
; #pragma unroll
;     for (int i = 0; i < 16; ++i) { LAS float* d = scr + (4 * i + r4) * 65 + c4; d[0] = v[i][0]; d[1] = v[i][1]; d[2] = v[i][2]; d[3] = v[i][3]; }
;     asm volatile("s_waitcnt lgkmcnt(0)" ::: "memory");
;     const int c = lane & 7;
; #pragma unroll
;     for (int j = 0; j < 8; ++j) { const int n = (lane >> 3) + 8 * j; const LAS float* s = scr + (8 * c) * 65 + n;
;         u32x4 o; o.x = cvt_pk_bf16(s[0 * 65], s[1 * 65]); o.y = cvt_pk_bf16(s[2 * 65], s[3 * 65]); o.z = cvt_pk_bf16(s[4 * 65], s[5 * 65]); o.w = cvt_pk_bf16(s[6 * 65], s[7 * 65]);
;         *(u32x4*)(WT + (size_t)(dn0 + (UPPERM ? ((n >> 5) * 64 + (n & 31)) : n)) * K + k0 + 8 * c) = o; }
; __device__ __forceinline__ void convert_range(const Params& p, LAS unsigned char* lds, int lo, int hi, int widx, int nw, int wave, int lane) {
;     LAS float* scr = (LAS float*)(lds + wave * 16640);
;     for (int it = lo + widx; it < hi; it += nw) {
.LBB0_29:
	s_cmpk_gt_i32 s22, 0x11ff
	s_cbranch_scc1 .LBB0_52
	s_mulk_i32 s20, 0x4100
	s_add_i32 s0, s20, 0
	v_lshrrev_b32_e32 v75, 3, v42
	v_and_b32_e32 v66, 56, v32
	v_lshrrev_b32_e32 v72, 4, v42
	s_waitcnt vmcnt(8)
	v_and_b32_e32 v0, 60, v34
	v_mul_u32_u24_e32 v1, 0x104, v66
	v_lshlrev_b32_e32 v2, 2, v75
	s_add_u32 s23, s10, 0x200000
	v_mov_b32_e32 v65, 0
	v_lshl_add_u32 v73, v0, 2, s0
	v_mul_u32_u24_e32 v74, 0x104, v72
	v_add3_u32 v76, s0, v1, v2
	v_or_b32_e32 v77, 8, v75
	v_or_b32_e32 v78, 16, v75
	v_or_b32_e32 v79, 24, v75
	v_or_b32_e32 v80, 32, v75
	v_or_b32_e32 v81, 40, v75
	v_or_b32_e32 v82, 48, v75
	v_or_b32_e32 v83, 56, v75
	v_bitop3_b32 v84, v75, 15, 40 bitop3:0xc8
	v_bitop3_b32 v85, v75, 23, 48 bitop3:0xc8
	v_bitop3_b32 v86, v75, 31, 56 bitop3:0xc8
	s_addc_u32 s24, s11, 0
	v_lshlrev_b32_e32 v64, 2, v0
	s_branch .LBB0_33

; __device__ __forceinline__ void convert_range(const Params& p, LAS unsigned char* lds, int lo, int hi, int widx, int nw, int wave, int lane) {
;     ...
;     for (int it = lo + widx; it < hi; it += nw) {
.LBB0_32:
	s_add_i32 s22, s22, s74
	s_cmpk_gt_i32 s22, 0x11ff
	s_cbranch_scc1 .LBB0_52

; #define LAS __attribute__((address_space(3)))
; __device__ __forceinline__ void convert_range(const Params& p, LAS unsigned char* lds, int lo, int hi, int widx, int nw, int wave, int lane) {
;     LAS float* scr = (LAS float*)(lds + wave * 16640);
;     for (int it = lo + widx; it < hi; it += nw) {
; __global__ void __launch_bounds__(NWAVES * 64, 2) mega_fwd(Params p) {
;     ...
;                 PHASE_IDS int idx, cnt; idle_workers(32 * (NIN / 256), G, bx, idx, cnt);
;                 if (idx >= 0) convert_range(p, lds, l == 0 ? CV_P0 : CV_B, l == 0 ? CV_A : CV_C, idx * NWAVES + wave, cnt * NWAVES, wave, lane);
.LBB0_358:
	v_readlane_b32 s0, v163, 1
	v_mov_b32_e32 v0, v240
	v_readlane_b32 s1, v163, 2
	s_andn2_b64 vcc, exec, s[0:1]
	v_readfirstlane_b32 s0, v0
	s_cbranch_vccnz .LBB0_387
	v_readlane_b32 s12, v163, 18
	s_ashr_i32 s0, s0, 6
	v_readlane_b32 s13, v163, 19
	s_and_b64 s[12:13], s[12:13], exec
	s_movk_i32 s1, 0x1200
	s_cselect_b32 s1, s1, 0x5440
	s_movk_i32 s12, 0x2f80
	s_cselect_b32 s22, s12, 0x69c0
	s_add_i32 s1, s0, s1
	v_readlane_b32 s12, v163, 3
	s_add_i32 s40, s1, s12
	s_cmp_ge_i32 s40, s22
	s_cbranch_scc1 .LBB0_387
	v_bfe_u32 v67, v0, 4, 2
	v_lshlrev_b32_e32 v2, 2, v0
	v_bfe_u32 v77, v0, 3, 3
	v_lshlrev_b32_e32 v0, 3, v0
	s_mulk_i32 s0, 0x4100
	v_and_b32_e32 v68, 56, v0
	s_add_i32 s0, s0, 0
	v_and_b32_e32 v66, 60, v2
	v_mul_u32_u24_e32 v0, 0x104, v68
	v_lshlrev_b32_e32 v2, 2, v77
	v_lshl_add_u32 v69, v66, 2, s0
	v_mul_u32_u24_e32 v76, 0x104, v67
	v_add3_u32 v78, s0, v0, v2
	v_or_b32_e32 v79, 8, v77
	v_or_b32_e32 v80, 16, v77
	v_or_b32_e32 v81, 24, v77
	v_or_b32_e32 v82, 32, v77
	v_or_b32_e32 v83, 40, v77
	v_or_b32_e32 v84, 48, v77
	v_or_b32_e32 v85, 56, v77
	v_bitop3_b32 v86, v77, 15, 40 bitop3:0xc8
	v_bitop3_b32 v87, v77, 23, 48 bitop3:0xc8
	v_bitop3_b32 v88, v77, 31, 56 bitop3:0xc8
	s_branch .LBB0_363

; #define LAS __attribute__((address_space(3)))
; __device__ __forceinline__ void convert_range(const Params& p, LAS unsigned char* lds, int lo, int hi, int widx, int nw, int wave, int lane) {
;     LAS float* scr = (LAS float*)(lds + wave * 16640);
;     for (int it = lo + widx; it < hi; it += nw) {
; __global__ void __launch_bounds__(NWAVES * 64, 2) mega_fwd(Params p) {
;     ...
;                 PHASE_IDS int idx, cnt; idle_workers(32 * (NUP / 256), G, bx, idx, cnt);
;                 if (idx >= 0) convert_range(p, lds, l == 0 ? CV_A : CV_C, l == 0 ? CV_B : 2 * I_L, idx * NWAVES + wave, cnt * NWAVES, wave, lane);
.LBB0_791:
	v_readlane_b32 s0, v163, 8
	v_mov_b32_e32 v0, v240
	v_readlane_b32 s1, v163, 9
	s_andn2_b64 vcc, exec, s[0:1]
	v_readfirstlane_b32 s0, v0
	v_readlane_b32 s52, v163, 34
	v_readlane_b32 s53, v163, 35
	s_movk_i32 s54, 0x2000
	s_movk_i32 s55, 0x4000
	s_movk_i32 s56, 0x6000
	s_mov_b32 s57, 0x18000
	s_mov_b32 s58, 0x8000
	s_mov_b32 s50, 0x30000
	s_cbranch_vccnz .LBB0_820
	v_readlane_b32 s12, v163, 18
	s_ashr_i32 s0, s0, 6
	v_readlane_b32 s13, v163, 19
	s_and_b64 s[12:13], s[12:13], exec
	s_movk_i32 s1, 0x2f80
	s_cselect_b32 s1, s1, 0x69c0
	s_movk_i32 s12, 0x7480
	s_cselect_b32 s22, 0x5440, s12
	s_add_i32 s1, s0, s1
	v_readlane_b32 s12, v163, 10
	s_add_i32 s42, s1, s12
	s_cmp_ge_i32 s42, s22
	s_cbranch_scc1 .LBB0_820
	v_bfe_u32 v67, v0, 4, 2
	v_lshlrev_b32_e32 v2, 2, v0
	v_bfe_u32 v77, v0, 3, 3
	v_lshlrev_b32_e32 v0, 3, v0
	s_mulk_i32 s0, 0x4100
	v_and_b32_e32 v68, 56, v0
	s_add_i32 s0, s0, 0
	v_and_b32_e32 v66, 60, v2
	v_mul_u32_u24_e32 v0, 0x104, v68
	v_lshlrev_b32_e32 v2, 2, v77
	v_lshl_add_u32 v69, v66, 2, s0
	v_mul_u32_u24_e32 v76, 0x104, v67
	v_add3_u32 v78, s0, v0, v2
	v_or_b32_e32 v79, 8, v77
	v_or_b32_e32 v80, 16, v77
	v_or_b32_e32 v81, 24, v77
	v_or_b32_e32 v82, 32, v77
	v_or_b32_e32 v83, 40, v77
	v_or_b32_e32 v84, 48, v77
	v_or_b32_e32 v85, 56, v77
	v_bitop3_b32 v86, v77, 15, 40 bitop3:0xc8
	v_bitop3_b32 v87, v77, 23, 48 bitop3:0xc8
	v_bitop3_b32 v88, v77, 31, 56 bitop3:0xc8
	s_branch .LBB0_796
